# down/out-proj/mix/F1/up GEMMs: each block's last unit of the phase stores its tile with sc1 (write-through) ahead of the grid barrier
# speedup vs baseline: 1.0004x; 1.0004x over previous
; __device__ __forceinline__ unsigned cvt_pk_bf16(float lo, float hi) { const f32x2 v = {lo, hi}; return __builtin_bit_cast(unsigned, __builtin_convertvector(v, bf16x2_t)); }
;     template <class Sched> __device__ __forceinline__ void operator()(const f32x4 (&acc)[2][2][4][2], const Unit& u, const Sched& S, int wr, int wc, int fr, int fq) const {
;     ...
;         if (kind == 0) {
;             bf16_t* base = (bf16_t*)uo;
; #pragma unroll
;             for (int ai = 0; ai < 2; ++ai)
; #pragma unroll
;                 for (int m = 0; m < 4; ++m) { bf16_t* rowp = base + (size_t)(rl0 + ai * HALF + m * 16) * ldo + cl0;
; #pragma unroll
;                     for (int bj = 0; bj < 2; ++bj) { const f32x4 v0 = acc[ai][bj][m][0], v1 = acc[ai][bj][m][1];
;                         u32x4 w; w.x = cvt_pk_bf16(v0[0], v0[1]); w.y = cvt_pk_bf16(v0[2], v0[3]); w.z = cvt_pk_bf16(v1[0], v1[1]); w.w = cvt_pk_bf16(v1[2], v1[3]);
;                         *(u32x4*)(rowp + bj * HALF) = w; } }
.Lepi_last_660:
	s_movk_i32 s17, 0x800
	v_lshl_add_u64 v[156:157], v[136:137], 1, s[4:5]
	v_mad_i64_i32 v[158:159], s[4:5], s17, v134, 0
	v_lshl_add_u64 v[158:159], v[158:159], 1, v[156:157]
	v_cvt_pk_bf16_f32 v108, v108, v109
	v_cvt_pk_bf16_f32 v109, v110, v111
	v_cvt_pk_bf16_f32 v110, v104, v105
	v_cvt_pk_bf16_f32 v111, v106, v107
	v_mad_i64_i32 v[104:105], s[4:5], s17, v138, 0
	v_cvt_pk_bf16_f32 v124, v124, v125
	v_cvt_pk_bf16_f32 v125, v126, v127
	v_cvt_pk_bf16_f32 v126, v120, v121
	v_cvt_pk_bf16_f32 v127, v122, v123
	global_store_dwordx4 v[158:159], v[108:111], off offset:256 sc1
	v_cvt_pk_bf16_f32 v92, v92, v93
	v_cvt_pk_bf16_f32 v93, v94, v95
	v_lshl_add_u64 v[108:109], v[104:105], 1, v[156:157]
	v_cvt_pk_bf16_f32 v94, v88, v89
	v_cvt_pk_bf16_f32 v95, v90, v91
	v_mad_i64_i32 v[88:89], s[4:5], s17, v140, 0
	global_store_dwordx4 v[158:159], v[124:127], off sc1
	v_cvt_pk_bf16_f32 v104, v116, v117
	v_cvt_pk_bf16_f32 v105, v118, v119
	v_cvt_pk_bf16_f32 v106, v112, v113
	v_cvt_pk_bf16_f32 v107, v114, v115
	global_store_dwordx4 v[108:109], v[92:95], off offset:256 sc1
	v_cvt_pk_bf16_f32 v76, v76, v77
	v_cvt_pk_bf16_f32 v77, v78, v79
	v_lshl_add_u64 v[92:93], v[88:89], 1, v[156:157]
	v_cvt_pk_bf16_f32 v78, v72, v73
	v_cvt_pk_bf16_f32 v79, v74, v75
	v_mad_i64_i32 v[72:73], s[4:5], s17, v142, 0
	v_cvt_pk_bf16_f32 v68, v68, v69
	v_cvt_pk_bf16_f32 v69, v70, v71
	v_cvt_pk_bf16_f32 v70, v64, v65
	v_mad_i64_i32 v[64:65], s[4:5], s17, v144, 0
	global_store_dwordx4 v[108:109], v[104:107], off sc1
	v_cvt_pk_bf16_f32 v88, v100, v101
	v_cvt_pk_bf16_f32 v89, v102, v103
	v_cvt_pk_bf16_f32 v90, v96, v97
	v_cvt_pk_bf16_f32 v91, v98, v99
	global_store_dwordx4 v[92:93], v[76:79], off offset:256 sc1
	v_cvt_pk_bf16_f32 v74, v80, v81
	v_cvt_pk_bf16_f32 v75, v82, v83
	v_lshl_add_u64 v[76:77], v[72:73], 1, v[156:157]
	v_cvt_pk_bf16_f32 v72, v84, v85
	v_cvt_pk_bf16_f32 v73, v86, v87
	v_cvt_pk_bf16_f32 v71, v66, v67
	v_lshl_add_u64 v[64:65], v[64:65], 1, v[156:157]
	v_cvt_pk_bf16_f32 v44, v44, v45
	v_cvt_pk_bf16_f32 v45, v46, v47
	v_cvt_pk_bf16_f32 v46, v40, v41
	v_cvt_pk_bf16_f32 v47, v42, v43
	v_mad_i64_i32 v[40:41], s[4:5], s17, v146, 0
	global_store_dwordx4 v[92:93], v[88:91], off sc1
	global_store_dwordx4 v[76:77], v[72:75], off sc1
	global_store_dwordx4 v[76:77], v[68:71], off offset:256 sc1
	v_cvt_pk_bf16_f32 v60, v60, v61
	v_cvt_pk_bf16_f32 v61, v62, v63
	v_cvt_pk_bf16_f32 v62, v56, v57
	v_cvt_pk_bf16_f32 v63, v58, v59
	global_store_dwordx4 v[64:65], v[44:47], off offset:256 sc1
	v_cvt_pk_bf16_f32 v28, v28, v29
	v_cvt_pk_bf16_f32 v29, v30, v31
	v_lshl_add_u64 v[44:45], v[40:41], 1, v[156:157]
	v_cvt_pk_bf16_f32 v30, v24, v25
	v_cvt_pk_bf16_f32 v31, v26, v27
	v_mad_i64_i32 v[24:25], s[4:5], s17, v148, 0
	global_store_dwordx4 v[64:65], v[60:63], off sc1
	v_cvt_pk_bf16_f32 v40, v52, v53
	v_cvt_pk_bf16_f32 v41, v54, v55
	v_cvt_pk_bf16_f32 v42, v48, v49
	v_cvt_pk_bf16_f32 v43, v50, v51
	global_store_dwordx4 v[44:45], v[28:31], off offset:256 sc1
	v_cvt_pk_bf16_f32 v12, v12, v13
	v_cvt_pk_bf16_f32 v13, v14, v15
	v_lshl_add_u64 v[28:29], v[24:25], 1, v[156:157]
	v_cvt_pk_bf16_f32 v14, v8, v9
	v_cvt_pk_bf16_f32 v15, v10, v11
	v_mad_i64_i32 v[8:9], s[4:5], s17, v150, 0
	global_store_dwordx4 v[44:45], v[40:43], off sc1
	v_cvt_pk_bf16_f32 v24, v36, v37
	v_cvt_pk_bf16_f32 v25, v38, v39
	v_cvt_pk_bf16_f32 v26, v32, v33
	v_cvt_pk_bf16_f32 v27, v34, v35
	global_store_dwordx4 v[28:29], v[12:15], off offset:256 sc1
	v_cvt_pk_bf16_f32 v10, v16, v17
	v_cvt_pk_bf16_f32 v11, v18, v19
	v_lshl_add_u64 v[12:13], v[8:9], 1, v[156:157]
	v_cvt_pk_bf16_f32 v8, v20, v21
	v_cvt_pk_bf16_f32 v9, v22, v23
	v_cvt_pk_bf16_f32 v4, v4, v5
	v_cvt_pk_bf16_f32 v5, v6, v7
	v_cvt_pk_bf16_f32 v6, v0, v1
	v_cvt_pk_bf16_f32 v7, v2, v3
	s_and_b64 vcc, exec, s[44:45]
	s_mov_b32 s38, s75
	s_mov_b32 s36, s40
	s_mov_b32 s34, s42
	s_mov_b64 s[96:97], s[48:49]
	s_mov_b64 s[94:95], s[46:47]
	global_store_dwordx4 v[28:29], v[24:27], off sc1
	global_store_dwordx4 v[12:13], v[8:11], off sc1
	global_store_dwordx4 v[12:13], v[4:7], off offset:256 sc1
	s_branch .LBB0_676
; __device__ __forceinline__ unsigned cvt_pk_bf16(float lo, float hi) { const f32x2 v = {lo, hi}; return __builtin_bit_cast(unsigned, __builtin_convertvector(v, bf16x2_t)); }
;     template <class Sched> __device__ __forceinline__ void operator()(const f32x4 (&acc)[2][2][4][2], const Unit& u, const Sched& S, int wr, int wc, int fr, int fq) const {
;     ...
;         if (kind == 0) {
;             bf16_t* base = (bf16_t*)uo;
; #pragma unroll
;             for (int ai = 0; ai < 2; ++ai)
; #pragma unroll
;                 for (int m = 0; m < 4; ++m) { bf16_t* rowp = base + (size_t)(rl0 + ai * HALF + m * 16) * ldo + cl0;
; #pragma unroll
;                     for (int bj = 0; bj < 2; ++bj) { const f32x4 v0 = acc[ai][bj][m][0], v1 = acc[ai][bj][m][1];
;                         u32x4 w; w.x = cvt_pk_bf16(v0[0], v0[1]); w.y = cvt_pk_bf16(v0[2], v0[3]); w.z = cvt_pk_bf16(v1[0], v1[1]); w.w = cvt_pk_bf16(v1[2], v1[3]);
;                         *(u32x4*)(rowp + bj * HALF) = w; } }
; template <class Epi, class Sched, bool ALIGN_EPI>
; __device__ __forceinline__ void gemm_phase(LAS unsigned char* lds, const int wid, const int lda_, const int ldb_, const int K_, const Sched& S, const Epi& E) {
;     ...
;         if (!has_next) break;
.LBB0_660:
	s_and_b64 vcc, exec, s[44:45]
	s_cbranch_vccnz .Lepi_last_660
	s_movk_i32 s17, 0x800
	v_lshl_add_u64 v[156:157], v[136:137], 1, s[4:5]
	v_mad_i64_i32 v[158:159], s[4:5], s17, v134, 0
	v_lshl_add_u64 v[158:159], v[158:159], 1, v[156:157]
	v_cvt_pk_bf16_f32 v108, v108, v109
	v_cvt_pk_bf16_f32 v109, v110, v111
	v_cvt_pk_bf16_f32 v110, v104, v105
	v_cvt_pk_bf16_f32 v111, v106, v107
	v_mad_i64_i32 v[104:105], s[4:5], s17, v138, 0
	v_cvt_pk_bf16_f32 v124, v124, v125
	v_cvt_pk_bf16_f32 v125, v126, v127
	v_cvt_pk_bf16_f32 v126, v120, v121
	v_cvt_pk_bf16_f32 v127, v122, v123
	global_store_dwordx4 v[158:159], v[108:111], off offset:256
	v_cvt_pk_bf16_f32 v92, v92, v93
	v_cvt_pk_bf16_f32 v93, v94, v95
	v_lshl_add_u64 v[108:109], v[104:105], 1, v[156:157]
	v_cvt_pk_bf16_f32 v94, v88, v89
	v_cvt_pk_bf16_f32 v95, v90, v91
	v_mad_i64_i32 v[88:89], s[4:5], s17, v140, 0
	global_store_dwordx4 v[158:159], v[124:127], off
	v_cvt_pk_bf16_f32 v104, v116, v117
	v_cvt_pk_bf16_f32 v105, v118, v119
	v_cvt_pk_bf16_f32 v106, v112, v113
	v_cvt_pk_bf16_f32 v107, v114, v115
	global_store_dwordx4 v[108:109], v[92:95], off offset:256
	v_cvt_pk_bf16_f32 v76, v76, v77
	v_cvt_pk_bf16_f32 v77, v78, v79
	v_lshl_add_u64 v[92:93], v[88:89], 1, v[156:157]
	v_cvt_pk_bf16_f32 v78, v72, v73
	v_cvt_pk_bf16_f32 v79, v74, v75
	v_mad_i64_i32 v[72:73], s[4:5], s17, v142, 0
	v_cvt_pk_bf16_f32 v68, v68, v69
	v_cvt_pk_bf16_f32 v69, v70, v71
	v_cvt_pk_bf16_f32 v70, v64, v65
	v_mad_i64_i32 v[64:65], s[4:5], s17, v144, 0
	global_store_dwordx4 v[108:109], v[104:107], off
	v_cvt_pk_bf16_f32 v88, v100, v101
	v_cvt_pk_bf16_f32 v89, v102, v103
	v_cvt_pk_bf16_f32 v90, v96, v97
	v_cvt_pk_bf16_f32 v91, v98, v99
	global_store_dwordx4 v[92:93], v[76:79], off offset:256
	v_cvt_pk_bf16_f32 v74, v80, v81
	v_cvt_pk_bf16_f32 v75, v82, v83
	v_lshl_add_u64 v[76:77], v[72:73], 1, v[156:157]
	v_cvt_pk_bf16_f32 v72, v84, v85
	v_cvt_pk_bf16_f32 v73, v86, v87
	v_cvt_pk_bf16_f32 v71, v66, v67
	v_lshl_add_u64 v[64:65], v[64:65], 1, v[156:157]
	v_cvt_pk_bf16_f32 v44, v44, v45
	v_cvt_pk_bf16_f32 v45, v46, v47
	v_cvt_pk_bf16_f32 v46, v40, v41
	v_cvt_pk_bf16_f32 v47, v42, v43
	v_mad_i64_i32 v[40:41], s[4:5], s17, v146, 0
	global_store_dwordx4 v[92:93], v[88:91], off
	global_store_dwordx4 v[76:77], v[72:75], off
	global_store_dwordx4 v[76:77], v[68:71], off offset:256
	v_cvt_pk_bf16_f32 v60, v60, v61
	v_cvt_pk_bf16_f32 v61, v62, v63
	v_cvt_pk_bf16_f32 v62, v56, v57
	v_cvt_pk_bf16_f32 v63, v58, v59
	global_store_dwordx4 v[64:65], v[44:47], off offset:256
	v_cvt_pk_bf16_f32 v28, v28, v29
	v_cvt_pk_bf16_f32 v29, v30, v31
	v_lshl_add_u64 v[44:45], v[40:41], 1, v[156:157]
	v_cvt_pk_bf16_f32 v30, v24, v25
	v_cvt_pk_bf16_f32 v31, v26, v27
	v_mad_i64_i32 v[24:25], s[4:5], s17, v148, 0
	global_store_dwordx4 v[64:65], v[60:63], off
	v_cvt_pk_bf16_f32 v40, v52, v53
	v_cvt_pk_bf16_f32 v41, v54, v55
	v_cvt_pk_bf16_f32 v42, v48, v49
	v_cvt_pk_bf16_f32 v43, v50, v51
	global_store_dwordx4 v[44:45], v[28:31], off offset:256
	v_cvt_pk_bf16_f32 v12, v12, v13
	v_cvt_pk_bf16_f32 v13, v14, v15
	v_lshl_add_u64 v[28:29], v[24:25], 1, v[156:157]
	v_cvt_pk_bf16_f32 v14, v8, v9
	v_cvt_pk_bf16_f32 v15, v10, v11
	v_mad_i64_i32 v[8:9], s[4:5], s17, v150, 0
	global_store_dwordx4 v[44:45], v[40:43], off
	v_cvt_pk_bf16_f32 v24, v36, v37
	v_cvt_pk_bf16_f32 v25, v38, v39
	v_cvt_pk_bf16_f32 v26, v32, v33
	v_cvt_pk_bf16_f32 v27, v34, v35
	global_store_dwordx4 v[28:29], v[12:15], off offset:256
	v_cvt_pk_bf16_f32 v10, v16, v17
	v_cvt_pk_bf16_f32 v11, v18, v19
	v_lshl_add_u64 v[12:13], v[8:9], 1, v[156:157]
	v_cvt_pk_bf16_f32 v8, v20, v21
	v_cvt_pk_bf16_f32 v9, v22, v23
	v_cvt_pk_bf16_f32 v4, v4, v5
	v_cvt_pk_bf16_f32 v5, v6, v7
	v_cvt_pk_bf16_f32 v6, v0, v1
	v_cvt_pk_bf16_f32 v7, v2, v3
	s_and_b64 vcc, exec, s[44:45]
	s_mov_b32 s38, s75
	s_mov_b32 s36, s40
	s_mov_b32 s34, s42
	s_mov_b64 s[96:97], s[48:49]
	s_mov_b64 s[94:95], s[46:47]
	global_store_dwordx4 v[28:29], v[24:27], off
	global_store_dwordx4 v[12:13], v[8:11], off
	global_store_dwordx4 v[12:13], v[4:7], off offset:256
	s_cbranch_vccnz .LBB0_676

; __device__ __forceinline__ unsigned cvt_pk_bf16(float lo, float hi) { const f32x2 v = {lo, hi}; return __builtin_bit_cast(unsigned, __builtin_convertvector(v, bf16x2_t)); }
;     template <class Sched> __device__ __forceinline__ void operator()(const f32x4 (&acc)[2][2][4][2], const Unit& u, const Sched& S, int wr, int wc, int fr, int fq) const {
;     ...
;         if (kind == 0) {
;             bf16_t* base = (bf16_t*)uo;
; #pragma unroll
;             for (int ai = 0; ai < 2; ++ai)
; #pragma unroll
;                 for (int m = 0; m < 4; ++m) { bf16_t* rowp = base + (size_t)(rl0 + ai * HALF + m * 16) * ldo + cl0;
; #pragma unroll
;                     for (int bj = 0; bj < 2; ++bj) { const f32x4 v0 = acc[ai][bj][m][0], v1 = acc[ai][bj][m][1];
;                         u32x4 w; w.x = cvt_pk_bf16(v0[0], v0[1]); w.y = cvt_pk_bf16(v0[2], v0[3]); w.z = cvt_pk_bf16(v1[0], v1[1]); w.w = cvt_pk_bf16(v1[2], v1[3]);
;                         *(u32x4*)(rowp + bj * HALF) = w; } }
.Lepi_last_693:
	v_lshl_add_u64 v[152:153], v[136:137], 1, s[4:5]
	v_mad_i64_i32 v[154:155], s[4:5], s31, v134, 0
	v_lshl_add_u64 v[154:155], v[154:155], 1, v[152:153]
	v_cvt_pk_bf16_f32 v108, v108, v109
	v_cvt_pk_bf16_f32 v109, v110, v111
	v_cvt_pk_bf16_f32 v110, v104, v105
	v_cvt_pk_bf16_f32 v111, v106, v107
	v_mad_i64_i32 v[104:105], s[4:5], s31, v138, 0
	v_cvt_pk_bf16_f32 v124, v124, v125
	v_cvt_pk_bf16_f32 v125, v126, v127
	v_cvt_pk_bf16_f32 v126, v120, v121
	v_cvt_pk_bf16_f32 v127, v122, v123
	global_store_dwordx4 v[154:155], v[108:111], off offset:256 sc1
	v_cvt_pk_bf16_f32 v92, v92, v93
	v_cvt_pk_bf16_f32 v93, v94, v95
	v_lshl_add_u64 v[108:109], v[104:105], 1, v[152:153]
	v_cvt_pk_bf16_f32 v94, v88, v89
	v_cvt_pk_bf16_f32 v95, v90, v91
	v_mad_i64_i32 v[88:89], s[4:5], s31, v140, 0
	global_store_dwordx4 v[154:155], v[124:127], off sc1
	v_cvt_pk_bf16_f32 v104, v116, v117
	v_cvt_pk_bf16_f32 v105, v118, v119
	v_cvt_pk_bf16_f32 v106, v112, v113
	v_cvt_pk_bf16_f32 v107, v114, v115
	global_store_dwordx4 v[108:109], v[92:95], off offset:256 sc1
	v_cvt_pk_bf16_f32 v76, v76, v77
	v_cvt_pk_bf16_f32 v77, v78, v79
	v_lshl_add_u64 v[92:93], v[88:89], 1, v[152:153]
	v_cvt_pk_bf16_f32 v78, v72, v73
	v_cvt_pk_bf16_f32 v79, v74, v75
	v_mad_i64_i32 v[72:73], s[4:5], s31, v142, 0
	v_cvt_pk_bf16_f32 v68, v68, v69
	v_cvt_pk_bf16_f32 v69, v70, v71
	v_cvt_pk_bf16_f32 v70, v64, v65
	v_mad_i64_i32 v[64:65], s[4:5], s31, v144, 0
	global_store_dwordx4 v[108:109], v[104:107], off sc1
	v_cvt_pk_bf16_f32 v88, v100, v101
	v_cvt_pk_bf16_f32 v89, v102, v103
	v_cvt_pk_bf16_f32 v90, v96, v97
	v_cvt_pk_bf16_f32 v91, v98, v99
	global_store_dwordx4 v[92:93], v[76:79], off offset:256 sc1
	v_cvt_pk_bf16_f32 v74, v80, v81
	v_cvt_pk_bf16_f32 v75, v82, v83
	v_lshl_add_u64 v[76:77], v[72:73], 1, v[152:153]
	v_cvt_pk_bf16_f32 v72, v84, v85
	v_cvt_pk_bf16_f32 v73, v86, v87
	v_cvt_pk_bf16_f32 v71, v66, v67
	v_lshl_add_u64 v[64:65], v[64:65], 1, v[152:153]
	v_cvt_pk_bf16_f32 v44, v44, v45
	v_cvt_pk_bf16_f32 v45, v46, v47
	v_cvt_pk_bf16_f32 v46, v40, v41
	v_cvt_pk_bf16_f32 v47, v42, v43
	v_mad_i64_i32 v[40:41], s[4:5], s31, v146, 0
	global_store_dwordx4 v[92:93], v[88:91], off sc1
	global_store_dwordx4 v[76:77], v[72:75], off sc1
	global_store_dwordx4 v[76:77], v[68:71], off offset:256 sc1
	v_cvt_pk_bf16_f32 v60, v60, v61
	v_cvt_pk_bf16_f32 v61, v62, v63
	v_cvt_pk_bf16_f32 v62, v56, v57
	v_cvt_pk_bf16_f32 v63, v58, v59
	global_store_dwordx4 v[64:65], v[44:47], off offset:256 sc1
	v_cvt_pk_bf16_f32 v28, v28, v29
	v_cvt_pk_bf16_f32 v29, v30, v31
	v_lshl_add_u64 v[44:45], v[40:41], 1, v[152:153]
	v_cvt_pk_bf16_f32 v30, v24, v25
	v_cvt_pk_bf16_f32 v31, v26, v27
	v_mad_i64_i32 v[24:25], s[4:5], s31, v148, 0
	global_store_dwordx4 v[64:65], v[60:63], off sc1
	v_cvt_pk_bf16_f32 v40, v52, v53
	v_cvt_pk_bf16_f32 v41, v54, v55
	v_cvt_pk_bf16_f32 v42, v48, v49
	v_cvt_pk_bf16_f32 v43, v50, v51
	global_store_dwordx4 v[44:45], v[28:31], off offset:256 sc1
	v_cvt_pk_bf16_f32 v12, v12, v13
	v_cvt_pk_bf16_f32 v13, v14, v15
	v_lshl_add_u64 v[28:29], v[24:25], 1, v[152:153]
	v_cvt_pk_bf16_f32 v14, v8, v9
	v_cvt_pk_bf16_f32 v15, v10, v11
	v_mad_i64_i32 v[8:9], s[4:5], s31, v150, 0
	global_store_dwordx4 v[44:45], v[40:43], off sc1
	v_cvt_pk_bf16_f32 v24, v36, v37
	v_cvt_pk_bf16_f32 v25, v38, v39
	v_cvt_pk_bf16_f32 v26, v32, v33
	v_cvt_pk_bf16_f32 v27, v34, v35
	global_store_dwordx4 v[28:29], v[12:15], off offset:256 sc1
	v_cvt_pk_bf16_f32 v10, v16, v17
	v_cvt_pk_bf16_f32 v11, v18, v19
	v_lshl_add_u64 v[12:13], v[8:9], 1, v[152:153]
	v_cvt_pk_bf16_f32 v8, v20, v21
	v_cvt_pk_bf16_f32 v9, v22, v23
	v_cvt_pk_bf16_f32 v4, v4, v5
	v_cvt_pk_bf16_f32 v5, v6, v7
	v_cvt_pk_bf16_f32 v6, v0, v1
	v_cvt_pk_bf16_f32 v7, v2, v3
	s_and_b64 vcc, exec, s[38:39]
	s_mov_b32 s74, s30
	s_mov_b32 s75, s73
	s_mov_b64 s[40:41], s[36:37]
	s_mov_b64 s[44:45], s[34:35]
	global_store_dwordx4 v[28:29], v[24:27], off sc1
	global_store_dwordx4 v[12:13], v[8:11], off sc1
	global_store_dwordx4 v[12:13], v[4:7], off offset:256 sc1
	s_branch .LBB0_710
; __device__ __forceinline__ unsigned cvt_pk_bf16(float lo, float hi) { const f32x2 v = {lo, hi}; return __builtin_bit_cast(unsigned, __builtin_convertvector(v, bf16x2_t)); }
;     template <class Sched> __device__ __forceinline__ void operator()(const f32x4 (&acc)[2][2][4][2], const Unit& u, const Sched& S, int wr, int wc, int fr, int fq) const {
;     ...
;         if (kind == 0) {
;             bf16_t* base = (bf16_t*)uo;
; #pragma unroll
;             for (int ai = 0; ai < 2; ++ai)
; #pragma unroll
;                 for (int m = 0; m < 4; ++m) { bf16_t* rowp = base + (size_t)(rl0 + ai * HALF + m * 16) * ldo + cl0;
; #pragma unroll
;                     for (int bj = 0; bj < 2; ++bj) { const f32x4 v0 = acc[ai][bj][m][0], v1 = acc[ai][bj][m][1];
;                         u32x4 w; w.x = cvt_pk_bf16(v0[0], v0[1]); w.y = cvt_pk_bf16(v0[2], v0[3]); w.z = cvt_pk_bf16(v1[0], v1[1]); w.w = cvt_pk_bf16(v1[2], v1[3]);
;                         *(u32x4*)(rowp + bj * HALF) = w; } }
; template <class Epi, class Sched, bool ALIGN_EPI>
; __device__ __forceinline__ void gemm_phase(LAS unsigned char* lds, const int wid, const int lda_, const int ldb_, const int K_, const Sched& S, const Epi& E) {
;     ...
;         if (!has_next) break;
.LBB0_693:
	s_and_b64 vcc, exec, s[38:39]
	s_cbranch_vccnz .Lepi_last_693
	v_lshl_add_u64 v[152:153], v[136:137], 1, s[4:5]
	v_mad_i64_i32 v[154:155], s[4:5], s31, v134, 0
	v_lshl_add_u64 v[154:155], v[154:155], 1, v[152:153]
	v_cvt_pk_bf16_f32 v108, v108, v109
	v_cvt_pk_bf16_f32 v109, v110, v111
	v_cvt_pk_bf16_f32 v110, v104, v105
	v_cvt_pk_bf16_f32 v111, v106, v107
	v_mad_i64_i32 v[104:105], s[4:5], s31, v138, 0
	v_cvt_pk_bf16_f32 v124, v124, v125
	v_cvt_pk_bf16_f32 v125, v126, v127
	v_cvt_pk_bf16_f32 v126, v120, v121
	v_cvt_pk_bf16_f32 v127, v122, v123
	global_store_dwordx4 v[154:155], v[108:111], off offset:256
	v_cvt_pk_bf16_f32 v92, v92, v93
	v_cvt_pk_bf16_f32 v93, v94, v95
	v_lshl_add_u64 v[108:109], v[104:105], 1, v[152:153]
	v_cvt_pk_bf16_f32 v94, v88, v89
	v_cvt_pk_bf16_f32 v95, v90, v91
	v_mad_i64_i32 v[88:89], s[4:5], s31, v140, 0
	global_store_dwordx4 v[154:155], v[124:127], off
	v_cvt_pk_bf16_f32 v104, v116, v117
	v_cvt_pk_bf16_f32 v105, v118, v119
	v_cvt_pk_bf16_f32 v106, v112, v113
	v_cvt_pk_bf16_f32 v107, v114, v115
	global_store_dwordx4 v[108:109], v[92:95], off offset:256
	v_cvt_pk_bf16_f32 v76, v76, v77
	v_cvt_pk_bf16_f32 v77, v78, v79
	v_lshl_add_u64 v[92:93], v[88:89], 1, v[152:153]
	v_cvt_pk_bf16_f32 v78, v72, v73
	v_cvt_pk_bf16_f32 v79, v74, v75
	v_mad_i64_i32 v[72:73], s[4:5], s31, v142, 0
	v_cvt_pk_bf16_f32 v68, v68, v69
	v_cvt_pk_bf16_f32 v69, v70, v71
	v_cvt_pk_bf16_f32 v70, v64, v65
	v_mad_i64_i32 v[64:65], s[4:5], s31, v144, 0
	global_store_dwordx4 v[108:109], v[104:107], off
	v_cvt_pk_bf16_f32 v88, v100, v101
	v_cvt_pk_bf16_f32 v89, v102, v103
	v_cvt_pk_bf16_f32 v90, v96, v97
	v_cvt_pk_bf16_f32 v91, v98, v99
	global_store_dwordx4 v[92:93], v[76:79], off offset:256
	v_cvt_pk_bf16_f32 v74, v80, v81
	v_cvt_pk_bf16_f32 v75, v82, v83
	v_lshl_add_u64 v[76:77], v[72:73], 1, v[152:153]
	v_cvt_pk_bf16_f32 v72, v84, v85
	v_cvt_pk_bf16_f32 v73, v86, v87
	v_cvt_pk_bf16_f32 v71, v66, v67
	v_lshl_add_u64 v[64:65], v[64:65], 1, v[152:153]
	v_cvt_pk_bf16_f32 v44, v44, v45
	v_cvt_pk_bf16_f32 v45, v46, v47
	v_cvt_pk_bf16_f32 v46, v40, v41
	v_cvt_pk_bf16_f32 v47, v42, v43
	v_mad_i64_i32 v[40:41], s[4:5], s31, v146, 0
	global_store_dwordx4 v[92:93], v[88:91], off
	global_store_dwordx4 v[76:77], v[72:75], off
	global_store_dwordx4 v[76:77], v[68:71], off offset:256
	v_cvt_pk_bf16_f32 v60, v60, v61
	v_cvt_pk_bf16_f32 v61, v62, v63
	v_cvt_pk_bf16_f32 v62, v56, v57
	v_cvt_pk_bf16_f32 v63, v58, v59
	global_store_dwordx4 v[64:65], v[44:47], off offset:256
	v_cvt_pk_bf16_f32 v28, v28, v29
	v_cvt_pk_bf16_f32 v29, v30, v31
	v_lshl_add_u64 v[44:45], v[40:41], 1, v[152:153]
	v_cvt_pk_bf16_f32 v30, v24, v25
	v_cvt_pk_bf16_f32 v31, v26, v27
	v_mad_i64_i32 v[24:25], s[4:5], s31, v148, 0
	global_store_dwordx4 v[64:65], v[60:63], off
	v_cvt_pk_bf16_f32 v40, v52, v53
	v_cvt_pk_bf16_f32 v41, v54, v55
	v_cvt_pk_bf16_f32 v42, v48, v49
	v_cvt_pk_bf16_f32 v43, v50, v51
	global_store_dwordx4 v[44:45], v[28:31], off offset:256
	v_cvt_pk_bf16_f32 v12, v12, v13
	v_cvt_pk_bf16_f32 v13, v14, v15
	v_lshl_add_u64 v[28:29], v[24:25], 1, v[152:153]
	v_cvt_pk_bf16_f32 v14, v8, v9
	v_cvt_pk_bf16_f32 v15, v10, v11
	v_mad_i64_i32 v[8:9], s[4:5], s31, v150, 0
	global_store_dwordx4 v[44:45], v[40:43], off
	v_cvt_pk_bf16_f32 v24, v36, v37
	v_cvt_pk_bf16_f32 v25, v38, v39
	v_cvt_pk_bf16_f32 v26, v32, v33
	v_cvt_pk_bf16_f32 v27, v34, v35
	global_store_dwordx4 v[28:29], v[12:15], off offset:256
	v_cvt_pk_bf16_f32 v10, v16, v17
	v_cvt_pk_bf16_f32 v11, v18, v19
	v_lshl_add_u64 v[12:13], v[8:9], 1, v[152:153]
	v_cvt_pk_bf16_f32 v8, v20, v21
	v_cvt_pk_bf16_f32 v9, v22, v23
	v_cvt_pk_bf16_f32 v4, v4, v5
	v_cvt_pk_bf16_f32 v5, v6, v7
	v_cvt_pk_bf16_f32 v6, v0, v1
	v_cvt_pk_bf16_f32 v7, v2, v3
	s_and_b64 vcc, exec, s[38:39]
	s_mov_b32 s74, s30
	s_mov_b32 s75, s73
	s_mov_b64 s[40:41], s[36:37]
	s_mov_b64 s[44:45], s[34:35]
	global_store_dwordx4 v[28:29], v[24:27], off
	global_store_dwordx4 v[12:13], v[8:11], off
	global_store_dwordx4 v[12:13], v[4:7], off offset:256
	s_cbranch_vccnz .LBB0_710

; __device__ __forceinline__ unsigned cvt_pk_bf16(float lo, float hi) { const f32x2 v = {lo, hi}; return __builtin_bit_cast(unsigned, __builtin_convertvector(v, bf16x2_t)); }
;     template <class Sched> __device__ __forceinline__ void operator()(const f32x4 (&acc)[2][2][4][2], const Unit& u, const Sched& S, int wr, int wc, int fr, int fq) const {
;     ...
;         if (kind == 0) {
;             bf16_t* base = (bf16_t*)uo;
; #pragma unroll
;             for (int ai = 0; ai < 2; ++ai)
; #pragma unroll
;                 for (int m = 0; m < 4; ++m) { bf16_t* rowp = base + (size_t)(rl0 + ai * HALF + m * 16) * ldo + cl0;
; #pragma unroll
;                     for (int bj = 0; bj < 2; ++bj) { const f32x4 v0 = acc[ai][bj][m][0], v1 = acc[ai][bj][m][1];
;                         u32x4 w; w.x = cvt_pk_bf16(v0[0], v0[1]); w.y = cvt_pk_bf16(v0[2], v0[3]); w.z = cvt_pk_bf16(v1[0], v1[1]); w.w = cvt_pk_bf16(v1[2], v1[3]);
;                         *(u32x4*)(rowp + bj * HALF) = w; } }
.Lepi_last_951:
	s_movk_i32 s17, 0x800
	v_lshl_add_u64 v[156:157], v[136:137], 1, s[4:5]
	v_mad_i64_i32 v[158:159], s[4:5], s17, v134, 0
	v_lshl_add_u64 v[158:159], v[158:159], 1, v[156:157]
	v_cvt_pk_bf16_f32 v108, v108, v109
	v_cvt_pk_bf16_f32 v109, v110, v111
	v_cvt_pk_bf16_f32 v110, v104, v105
	v_cvt_pk_bf16_f32 v111, v106, v107
	v_mad_i64_i32 v[104:105], s[4:5], s17, v138, 0
	v_cvt_pk_bf16_f32 v124, v124, v125
	v_cvt_pk_bf16_f32 v125, v126, v127
	v_cvt_pk_bf16_f32 v126, v120, v121
	v_cvt_pk_bf16_f32 v127, v122, v123
	global_store_dwordx4 v[158:159], v[108:111], off offset:256 sc1
	v_cvt_pk_bf16_f32 v92, v92, v93
	v_cvt_pk_bf16_f32 v93, v94, v95
	v_lshl_add_u64 v[108:109], v[104:105], 1, v[156:157]
	v_cvt_pk_bf16_f32 v94, v88, v89
	v_cvt_pk_bf16_f32 v95, v90, v91
	v_mad_i64_i32 v[88:89], s[4:5], s17, v140, 0
	global_store_dwordx4 v[158:159], v[124:127], off sc1
	v_cvt_pk_bf16_f32 v104, v116, v117
	v_cvt_pk_bf16_f32 v105, v118, v119
	v_cvt_pk_bf16_f32 v106, v112, v113
	v_cvt_pk_bf16_f32 v107, v114, v115
	global_store_dwordx4 v[108:109], v[92:95], off offset:256 sc1
	v_cvt_pk_bf16_f32 v76, v76, v77
	v_cvt_pk_bf16_f32 v77, v78, v79
	v_lshl_add_u64 v[92:93], v[88:89], 1, v[156:157]
	v_cvt_pk_bf16_f32 v78, v72, v73
	v_cvt_pk_bf16_f32 v79, v74, v75
	v_mad_i64_i32 v[72:73], s[4:5], s17, v142, 0
	v_cvt_pk_bf16_f32 v68, v68, v69
	v_cvt_pk_bf16_f32 v69, v70, v71
	v_cvt_pk_bf16_f32 v70, v64, v65
	v_mad_i64_i32 v[64:65], s[4:5], s17, v144, 0
	global_store_dwordx4 v[108:109], v[104:107], off sc1
	v_cvt_pk_bf16_f32 v88, v100, v101
	v_cvt_pk_bf16_f32 v89, v102, v103
	v_cvt_pk_bf16_f32 v90, v96, v97
	v_cvt_pk_bf16_f32 v91, v98, v99
	global_store_dwordx4 v[92:93], v[76:79], off offset:256 sc1
	v_cvt_pk_bf16_f32 v74, v80, v81
	v_cvt_pk_bf16_f32 v75, v82, v83
	v_lshl_add_u64 v[76:77], v[72:73], 1, v[156:157]
	v_cvt_pk_bf16_f32 v72, v84, v85
	v_cvt_pk_bf16_f32 v73, v86, v87
	v_cvt_pk_bf16_f32 v71, v66, v67
	v_lshl_add_u64 v[64:65], v[64:65], 1, v[156:157]
	v_cvt_pk_bf16_f32 v44, v44, v45
	v_cvt_pk_bf16_f32 v45, v46, v47
	v_cvt_pk_bf16_f32 v46, v40, v41
	v_cvt_pk_bf16_f32 v47, v42, v43
	v_mad_i64_i32 v[40:41], s[4:5], s17, v146, 0
	global_store_dwordx4 v[92:93], v[88:91], off sc1
	global_store_dwordx4 v[76:77], v[72:75], off sc1
	global_store_dwordx4 v[76:77], v[68:71], off offset:256 sc1
	v_cvt_pk_bf16_f32 v60, v60, v61
	v_cvt_pk_bf16_f32 v61, v62, v63
	v_cvt_pk_bf16_f32 v62, v56, v57
	v_cvt_pk_bf16_f32 v63, v58, v59
	global_store_dwordx4 v[64:65], v[44:47], off offset:256 sc1
	v_cvt_pk_bf16_f32 v28, v28, v29
	v_cvt_pk_bf16_f32 v29, v30, v31
	v_lshl_add_u64 v[44:45], v[40:41], 1, v[156:157]
	v_cvt_pk_bf16_f32 v30, v24, v25
	v_cvt_pk_bf16_f32 v31, v26, v27
	v_mad_i64_i32 v[24:25], s[4:5], s17, v148, 0
	global_store_dwordx4 v[64:65], v[60:63], off sc1
	v_cvt_pk_bf16_f32 v40, v52, v53
	v_cvt_pk_bf16_f32 v41, v54, v55
	v_cvt_pk_bf16_f32 v42, v48, v49
	v_cvt_pk_bf16_f32 v43, v50, v51
	global_store_dwordx4 v[44:45], v[28:31], off offset:256 sc1
	v_cvt_pk_bf16_f32 v12, v12, v13
	v_cvt_pk_bf16_f32 v13, v14, v15
	v_lshl_add_u64 v[28:29], v[24:25], 1, v[156:157]
	v_cvt_pk_bf16_f32 v14, v8, v9
	v_cvt_pk_bf16_f32 v15, v10, v11
	v_mad_i64_i32 v[8:9], s[4:5], s17, v150, 0
	global_store_dwordx4 v[44:45], v[40:43], off sc1
	v_cvt_pk_bf16_f32 v24, v36, v37
	v_cvt_pk_bf16_f32 v25, v38, v39
	v_cvt_pk_bf16_f32 v26, v32, v33
	v_cvt_pk_bf16_f32 v27, v34, v35
	global_store_dwordx4 v[28:29], v[12:15], off offset:256 sc1
	v_cvt_pk_bf16_f32 v10, v16, v17
	v_cvt_pk_bf16_f32 v11, v18, v19
	v_lshl_add_u64 v[12:13], v[8:9], 1, v[156:157]
	v_cvt_pk_bf16_f32 v8, v20, v21
	v_cvt_pk_bf16_f32 v9, v22, v23
	v_cvt_pk_bf16_f32 v4, v4, v5
	v_cvt_pk_bf16_f32 v5, v6, v7
	v_cvt_pk_bf16_f32 v6, v0, v1
	v_cvt_pk_bf16_f32 v7, v2, v3
	s_and_b64 vcc, exec, s[36:37]
	s_mov_b32 s48, s75
	s_mov_b32 s44, s30
	s_mov_b32 s46, s34
	s_mov_b64 s[96:97], s[40:41]
	s_mov_b64 s[94:95], s[38:39]
	global_store_dwordx4 v[28:29], v[24:27], off sc1
	global_store_dwordx4 v[12:13], v[8:11], off sc1
	global_store_dwordx4 v[12:13], v[4:7], off offset:256 sc1
	s_branch .LBB0_967
; __device__ __forceinline__ unsigned cvt_pk_bf16(float lo, float hi) { const f32x2 v = {lo, hi}; return __builtin_bit_cast(unsigned, __builtin_convertvector(v, bf16x2_t)); }
;     template <class Sched> __device__ __forceinline__ void operator()(const f32x4 (&acc)[2][2][4][2], const Unit& u, const Sched& S, int wr, int wc, int fr, int fq) const {
;     ...
;         if (kind == 0) {
;             bf16_t* base = (bf16_t*)uo;
; #pragma unroll
;             for (int ai = 0; ai < 2; ++ai)
; #pragma unroll
;                 for (int m = 0; m < 4; ++m) { bf16_t* rowp = base + (size_t)(rl0 + ai * HALF + m * 16) * ldo + cl0;
; #pragma unroll
;                     for (int bj = 0; bj < 2; ++bj) { const f32x4 v0 = acc[ai][bj][m][0], v1 = acc[ai][bj][m][1];
;                         u32x4 w; w.x = cvt_pk_bf16(v0[0], v0[1]); w.y = cvt_pk_bf16(v0[2], v0[3]); w.z = cvt_pk_bf16(v1[0], v1[1]); w.w = cvt_pk_bf16(v1[2], v1[3]);
;                         *(u32x4*)(rowp + bj * HALF) = w; } }
; template <class Epi, class Sched, bool ALIGN_EPI>
; __device__ __forceinline__ void gemm_phase(LAS unsigned char* lds, const int wid, const int lda_, const int ldb_, const int K_, const Sched& S, const Epi& E) {
;     ...
;         if (!has_next) break;
.LBB0_951:
	s_and_b64 vcc, exec, s[36:37]
	s_cbranch_vccnz .Lepi_last_951
	s_movk_i32 s17, 0x800
	v_lshl_add_u64 v[156:157], v[136:137], 1, s[4:5]
	v_mad_i64_i32 v[158:159], s[4:5], s17, v134, 0
	v_lshl_add_u64 v[158:159], v[158:159], 1, v[156:157]
	v_cvt_pk_bf16_f32 v108, v108, v109
	v_cvt_pk_bf16_f32 v109, v110, v111
	v_cvt_pk_bf16_f32 v110, v104, v105
	v_cvt_pk_bf16_f32 v111, v106, v107
	v_mad_i64_i32 v[104:105], s[4:5], s17, v138, 0
	v_cvt_pk_bf16_f32 v124, v124, v125
	v_cvt_pk_bf16_f32 v125, v126, v127
	v_cvt_pk_bf16_f32 v126, v120, v121
	v_cvt_pk_bf16_f32 v127, v122, v123
	global_store_dwordx4 v[158:159], v[108:111], off offset:256
	v_cvt_pk_bf16_f32 v92, v92, v93
	v_cvt_pk_bf16_f32 v93, v94, v95
	v_lshl_add_u64 v[108:109], v[104:105], 1, v[156:157]
	v_cvt_pk_bf16_f32 v94, v88, v89
	v_cvt_pk_bf16_f32 v95, v90, v91
	v_mad_i64_i32 v[88:89], s[4:5], s17, v140, 0
	global_store_dwordx4 v[158:159], v[124:127], off
	v_cvt_pk_bf16_f32 v104, v116, v117
	v_cvt_pk_bf16_f32 v105, v118, v119
	v_cvt_pk_bf16_f32 v106, v112, v113
	v_cvt_pk_bf16_f32 v107, v114, v115
	global_store_dwordx4 v[108:109], v[92:95], off offset:256
	v_cvt_pk_bf16_f32 v76, v76, v77
	v_cvt_pk_bf16_f32 v77, v78, v79
	v_lshl_add_u64 v[92:93], v[88:89], 1, v[156:157]
	v_cvt_pk_bf16_f32 v78, v72, v73
	v_cvt_pk_bf16_f32 v79, v74, v75
	v_mad_i64_i32 v[72:73], s[4:5], s17, v142, 0
	v_cvt_pk_bf16_f32 v68, v68, v69
	v_cvt_pk_bf16_f32 v69, v70, v71
	v_cvt_pk_bf16_f32 v70, v64, v65
	v_mad_i64_i32 v[64:65], s[4:5], s17, v144, 0
	global_store_dwordx4 v[108:109], v[104:107], off
	v_cvt_pk_bf16_f32 v88, v100, v101
	v_cvt_pk_bf16_f32 v89, v102, v103
	v_cvt_pk_bf16_f32 v90, v96, v97
	v_cvt_pk_bf16_f32 v91, v98, v99
	global_store_dwordx4 v[92:93], v[76:79], off offset:256
	v_cvt_pk_bf16_f32 v74, v80, v81
	v_cvt_pk_bf16_f32 v75, v82, v83
	v_lshl_add_u64 v[76:77], v[72:73], 1, v[156:157]
	v_cvt_pk_bf16_f32 v72, v84, v85
	v_cvt_pk_bf16_f32 v73, v86, v87
	v_cvt_pk_bf16_f32 v71, v66, v67
	v_lshl_add_u64 v[64:65], v[64:65], 1, v[156:157]
	v_cvt_pk_bf16_f32 v44, v44, v45
	v_cvt_pk_bf16_f32 v45, v46, v47
	v_cvt_pk_bf16_f32 v46, v40, v41
	v_cvt_pk_bf16_f32 v47, v42, v43
	v_mad_i64_i32 v[40:41], s[4:5], s17, v146, 0
	global_store_dwordx4 v[92:93], v[88:91], off
	global_store_dwordx4 v[76:77], v[72:75], off
	global_store_dwordx4 v[76:77], v[68:71], off offset:256
	v_cvt_pk_bf16_f32 v60, v60, v61
	v_cvt_pk_bf16_f32 v61, v62, v63
	v_cvt_pk_bf16_f32 v62, v56, v57
	v_cvt_pk_bf16_f32 v63, v58, v59
	global_store_dwordx4 v[64:65], v[44:47], off offset:256
	v_cvt_pk_bf16_f32 v28, v28, v29
	v_cvt_pk_bf16_f32 v29, v30, v31
	v_lshl_add_u64 v[44:45], v[40:41], 1, v[156:157]
	v_cvt_pk_bf16_f32 v30, v24, v25
	v_cvt_pk_bf16_f32 v31, v26, v27
	v_mad_i64_i32 v[24:25], s[4:5], s17, v148, 0
	global_store_dwordx4 v[64:65], v[60:63], off
	v_cvt_pk_bf16_f32 v40, v52, v53
	v_cvt_pk_bf16_f32 v41, v54, v55
	v_cvt_pk_bf16_f32 v42, v48, v49
	v_cvt_pk_bf16_f32 v43, v50, v51
	global_store_dwordx4 v[44:45], v[28:31], off offset:256
	v_cvt_pk_bf16_f32 v12, v12, v13
	v_cvt_pk_bf16_f32 v13, v14, v15
	v_lshl_add_u64 v[28:29], v[24:25], 1, v[156:157]
	v_cvt_pk_bf16_f32 v14, v8, v9
	v_cvt_pk_bf16_f32 v15, v10, v11
	v_mad_i64_i32 v[8:9], s[4:5], s17, v150, 0
	global_store_dwordx4 v[44:45], v[40:43], off
	v_cvt_pk_bf16_f32 v24, v36, v37
	v_cvt_pk_bf16_f32 v25, v38, v39
	v_cvt_pk_bf16_f32 v26, v32, v33
	v_cvt_pk_bf16_f32 v27, v34, v35
	global_store_dwordx4 v[28:29], v[12:15], off offset:256
	v_cvt_pk_bf16_f32 v10, v16, v17
	v_cvt_pk_bf16_f32 v11, v18, v19
	v_lshl_add_u64 v[12:13], v[8:9], 1, v[156:157]
	v_cvt_pk_bf16_f32 v8, v20, v21
	v_cvt_pk_bf16_f32 v9, v22, v23
	v_cvt_pk_bf16_f32 v4, v4, v5
	v_cvt_pk_bf16_f32 v5, v6, v7
	v_cvt_pk_bf16_f32 v6, v0, v1
	v_cvt_pk_bf16_f32 v7, v2, v3
	s_and_b64 vcc, exec, s[36:37]
	s_mov_b32 s48, s75
	s_mov_b32 s44, s30
	s_mov_b32 s46, s34
	s_mov_b64 s[96:97], s[40:41]
	s_mov_b64 s[94:95], s[38:39]
	global_store_dwordx4 v[28:29], v[24:27], off
	global_store_dwordx4 v[12:13], v[8:11], off
	global_store_dwordx4 v[12:13], v[4:7], off offset:256
	s_cbranch_vccnz .LBB0_967

; __device__ __forceinline__ unsigned cvt_pk_bf16(float lo, float hi) { const f32x2 v = {lo, hi}; return __builtin_bit_cast(unsigned, __builtin_convertvector(v, bf16x2_t)); }
;     template <class Sched> __device__ __forceinline__ void operator()(const f32x4 (&acc)[2][2][4][2], const Unit& u, const Sched& S, int wr, int wc, int fr, int fq) const {
;     ...
;         if (kind == 0) {
;             bf16_t* base = (bf16_t*)uo;
; #pragma unroll
;             for (int ai = 0; ai < 2; ++ai)
; #pragma unroll
;                 for (int m = 0; m < 4; ++m) { bf16_t* rowp = base + (size_t)(rl0 + ai * HALF + m * 16) * ldo + cl0;
; #pragma unroll
;                     for (int bj = 0; bj < 2; ++bj) { const f32x4 v0 = acc[ai][bj][m][0], v1 = acc[ai][bj][m][1];
;                         u32x4 w; w.x = cvt_pk_bf16(v0[0], v0[1]); w.y = cvt_pk_bf16(v0[2], v0[3]); w.z = cvt_pk_bf16(v1[0], v1[1]); w.w = cvt_pk_bf16(v1[2], v1[3]);
;                         *(u32x4*)(rowp + bj * HALF) = w; } }
.Lepi_last_1120:
	s_sub_i32 s4, s38, 22
	s_ashr_i32 s5, s38, 31
	s_cmp_lt_i32 s38, 22
	s_cselect_b32 s5, s5, 0
	s_cselect_b32 s4, s38, s4
	s_mov_b32 s17, 0x2bc00000
	s_cselect_b32 s17, 0x1f600000, s17
	s_lshl_b64 s[4:5], s[4:5], 9
	s_add_u32 s4, s66, s4
	s_addc_u32 s5, s67, s5
	s_add_u32 s4, s4, s17
	s_addc_u32 s5, s5, 0
	s_mul_i32 s27, s34, 0x2c0000
	s_mul_hi_i32 s17, s34, 0x2c0000
	s_add_u32 s4, s4, s27
	s_addc_u32 s5, s5, s17
	s_movk_i32 s17, 0x1600
	v_lshl_add_u64 v[156:157], v[136:137], 1, s[4:5]
	v_mad_i64_i32 v[158:159], s[4:5], s17, v134, 0
	v_lshl_add_u64 v[158:159], v[158:159], 1, v[156:157]
	v_cvt_pk_bf16_f32 v108, v108, v109
	v_cvt_pk_bf16_f32 v109, v110, v111
	v_cvt_pk_bf16_f32 v110, v104, v105
	v_cvt_pk_bf16_f32 v111, v106, v107
	v_mad_i64_i32 v[104:105], s[4:5], s17, v138, 0
	v_cvt_pk_bf16_f32 v124, v124, v125
	v_cvt_pk_bf16_f32 v125, v126, v127
	v_cvt_pk_bf16_f32 v126, v120, v121
	v_cvt_pk_bf16_f32 v127, v122, v123
	global_store_dwordx4 v[158:159], v[108:111], off offset:256 sc1
	v_cvt_pk_bf16_f32 v92, v92, v93
	v_cvt_pk_bf16_f32 v93, v94, v95
	v_lshl_add_u64 v[108:109], v[104:105], 1, v[156:157]
	v_cvt_pk_bf16_f32 v94, v88, v89
	v_cvt_pk_bf16_f32 v95, v90, v91
	v_mad_i64_i32 v[88:89], s[4:5], s17, v140, 0
	global_store_dwordx4 v[158:159], v[124:127], off sc1
	v_cvt_pk_bf16_f32 v104, v116, v117
	v_cvt_pk_bf16_f32 v105, v118, v119
	v_cvt_pk_bf16_f32 v106, v112, v113
	v_cvt_pk_bf16_f32 v107, v114, v115
	global_store_dwordx4 v[108:109], v[92:95], off offset:256 sc1
	v_cvt_pk_bf16_f32 v76, v76, v77
	v_cvt_pk_bf16_f32 v77, v78, v79
	v_lshl_add_u64 v[92:93], v[88:89], 1, v[156:157]
	v_cvt_pk_bf16_f32 v78, v72, v73
	v_cvt_pk_bf16_f32 v79, v74, v75
	v_mad_i64_i32 v[72:73], s[4:5], s17, v142, 0
	v_cvt_pk_bf16_f32 v68, v68, v69
	v_cvt_pk_bf16_f32 v69, v70, v71
	v_cvt_pk_bf16_f32 v70, v64, v65
	v_mad_i64_i32 v[64:65], s[4:5], s17, v144, 0
	global_store_dwordx4 v[108:109], v[104:107], off sc1
	v_cvt_pk_bf16_f32 v88, v100, v101
	v_cvt_pk_bf16_f32 v89, v102, v103
	v_cvt_pk_bf16_f32 v90, v96, v97
	v_cvt_pk_bf16_f32 v91, v98, v99
	global_store_dwordx4 v[92:93], v[76:79], off offset:256 sc1
	v_cvt_pk_bf16_f32 v74, v80, v81
	v_cvt_pk_bf16_f32 v75, v82, v83
	v_lshl_add_u64 v[76:77], v[72:73], 1, v[156:157]
	v_cvt_pk_bf16_f32 v72, v84, v85
	v_cvt_pk_bf16_f32 v73, v86, v87
	v_cvt_pk_bf16_f32 v71, v66, v67
	v_lshl_add_u64 v[64:65], v[64:65], 1, v[156:157]
	v_cvt_pk_bf16_f32 v44, v44, v45
	v_cvt_pk_bf16_f32 v45, v46, v47
	v_cvt_pk_bf16_f32 v46, v40, v41
	v_cvt_pk_bf16_f32 v47, v42, v43
	v_mad_i64_i32 v[40:41], s[4:5], s17, v146, 0
	global_store_dwordx4 v[92:93], v[88:91], off sc1
	global_store_dwordx4 v[76:77], v[72:75], off sc1
	global_store_dwordx4 v[76:77], v[68:71], off offset:256 sc1
	v_cvt_pk_bf16_f32 v60, v60, v61
	v_cvt_pk_bf16_f32 v61, v62, v63
	v_cvt_pk_bf16_f32 v62, v56, v57
	v_cvt_pk_bf16_f32 v63, v58, v59
	global_store_dwordx4 v[64:65], v[44:47], off offset:256 sc1
	v_cvt_pk_bf16_f32 v28, v28, v29
	v_cvt_pk_bf16_f32 v29, v30, v31
	v_lshl_add_u64 v[44:45], v[40:41], 1, v[156:157]
	v_cvt_pk_bf16_f32 v30, v24, v25
	v_cvt_pk_bf16_f32 v31, v26, v27
	v_mad_i64_i32 v[24:25], s[4:5], s17, v148, 0
	global_store_dwordx4 v[64:65], v[60:63], off sc1
	v_cvt_pk_bf16_f32 v40, v52, v53
	v_cvt_pk_bf16_f32 v41, v54, v55
	v_cvt_pk_bf16_f32 v42, v48, v49
	v_cvt_pk_bf16_f32 v43, v50, v51
	global_store_dwordx4 v[44:45], v[28:31], off offset:256 sc1
	v_cvt_pk_bf16_f32 v12, v12, v13
	v_cvt_pk_bf16_f32 v13, v14, v15
	v_lshl_add_u64 v[28:29], v[24:25], 1, v[156:157]
	v_cvt_pk_bf16_f32 v14, v8, v9
	v_cvt_pk_bf16_f32 v15, v10, v11
	v_mad_i64_i32 v[8:9], s[4:5], s17, v150, 0
	global_store_dwordx4 v[44:45], v[40:43], off sc1
	v_cvt_pk_bf16_f32 v24, v36, v37
	v_cvt_pk_bf16_f32 v25, v38, v39
	v_cvt_pk_bf16_f32 v26, v32, v33
	v_cvt_pk_bf16_f32 v27, v34, v35
	global_store_dwordx4 v[28:29], v[12:15], off offset:256 sc1
	v_cvt_pk_bf16_f32 v10, v16, v17
	v_cvt_pk_bf16_f32 v11, v18, v19
	v_lshl_add_u64 v[12:13], v[8:9], 1, v[156:157]
	v_cvt_pk_bf16_f32 v8, v20, v21
	v_cvt_pk_bf16_f32 v9, v22, v23
	v_cvt_pk_bf16_f32 v4, v4, v5
	v_cvt_pk_bf16_f32 v5, v6, v7
	v_cvt_pk_bf16_f32 v6, v0, v1
	v_cvt_pk_bf16_f32 v7, v2, v3
	s_and_b64 vcc, exec, s[36:37]
	s_mov_b32 s38, s42
	s_mov_b32 s34, s44
	s_mov_b64 s[50:51], s[48:49]
	s_mov_b64 s[40:41], s[46:47]
	global_store_dwordx4 v[28:29], v[24:27], off sc1
	global_store_dwordx4 v[12:13], v[8:11], off sc1
	global_store_dwordx4 v[12:13], v[4:7], off offset:256 sc1
	s_branch .Lepi_last_done_1120

; #define PG8_STAGE(bufoff, gbase, voff) do { _Pragma("unroll") for (int _i = 0; _i < 2; ++_i) \
;         __builtin_amdgcn_global_load_lds((const unsigned*)((const char*)(gbase) + (voff)[_i]), (LAS unsigned*)(lds + (bufoff) + ldsw + _i * 8192), 16, 0, 0); } while (0)
; #define PG8_LDA(dst, b, h) do { _Pragma("unroll") for (int m = 0; m < 4; ++m) _Pragma("unroll") for (int k = 0; k < 2; ++k) dst[m][k] = *(const LAS bf16x8*)(lds + PG8_SA(b, h) + aoff + m * 2048 + k * 1024); } while (0)
; #define PG8_LDB(dst, b, h) do { _Pragma("unroll") for (int n = 0; n < 2; ++n) _Pragma("unroll") for (int k = 0; k < 2; ++k) dst[n][k] = *(const LAS bf16x8*)(lds + PG8_SB(b, h) + boff + n * 2048 + k * 1024); } while (0)
; #define PG8_MMA(ai, bj, At, Bt) do { __builtin_amdgcn_s_setprio(1); _Pragma("unroll") for (int m = 0; m < 4; ++m) _Pragma("unroll") for (int n = 0; n < 2; ++n) _Pragma("unroll") for (int k = 0; k < 2; ++k) \
;         acc[ai][bj][m][n] = __builtin_amdgcn_mfma_f32_16x16x32_bf16(Bt[n][k], At[m][k], acc[ai][bj][m][n], 0, 0, 0); __builtin_amdgcn_s_setprio(0); } while (0)
; #define PG8_WAIT_V(n) asm volatile("s_waitcnt vmcnt(" #n ")" ::: "memory")
; #define PG8_WAIT_L(n) asm volatile("s_waitcnt lgkmcnt(" #n ")" ::: "memory")
; #define PG8_BAR __builtin_amdgcn_s_barrier()
; #define PG8_SCHED __builtin_amdgcn_sched_barrier(0)
; template <class Epi, class Sched, bool ALIGN_EPI>
; __device__ __forceinline__ void gemm_phase(LAS unsigned char* lds, const int wid, const int lda_, const int ldb_, const int K_, const Sched& S, const Epi& E) {
;     ...
;             PG8_LDB(B0, 1, 0); PG8_LDB(B1, 1, 1); PG8_SCHED; PG8_LDA(At, 1, 0); PG8_STAGE(PG8_SA(0, 1), a2 + hstepA, voffA);
;             PG8_WAIT_V(8); PG8_WAIT_L(0); PG8_BAR; PG8_MMA(0, 0, At, B0); PG8_MMA(0, 1, At, B1); PG8_BAR; PG8_SCHED;
;             PG8_LDA(At, 1, 1); PG8_STAGE(PG8_SB(1, 0), b3, voffB); PG8_STAGE(PG8_SB(1, 1), b3 + hstepB, voffB); PG8_STAGE(PG8_SA(1, 0), a3, voffA);
;             PG8_WAIT_V(8); PG8_WAIT_L(0); PG8_BAR; PG8_MMA(1, 0, At, B0); PG8_MMA(1, 1, At, B1); PG8_BAR; PG8_SCHED;
.Lgemm_join_1120:
	s_add_i32 s17, 0, 0x18000
	v_add_u32_e32 v141, s17, v135
	s_add_i32 s27, 0, 0x1c000
	ds_read_b128 v[160:163], v141
	ds_read_b128 v[164:167], v141 offset:1024
	ds_read_b128 v[168:171], v141 offset:2048
	ds_read_b128 v[172:175], v141 offset:3072
	v_add_u32_e32 v141, s27, v135
	ds_read_b128 v[180:183], v141
	ds_read_b128 v[184:187], v141 offset:1024
	ds_read_b128 v[188:191], v141 offset:2048
	ds_read_b128 v[192:195], v141 offset:3072
	s_add_u32 s80, s94, s10
	s_addc_u32 s81, s95, s11
	s_mov_b32 m0, s39
	v_lshl_add_u64 v[248:249], s[80:81], 0, v[132:133]
	ds_read_b128 v[196:199], v139 offset:32768
	ds_read_b128 v[200:203], v139 offset:33792
	ds_read_b128 v[204:207], v139 offset:34816
	ds_read_b128 v[208:211], v139 offset:35840
	ds_read_b128 v[212:215], v139 offset:36864
	ds_read_b128 v[216:219], v139 offset:37888
	ds_read_b128 v[220:223], v139 offset:38912
	ds_read_b128 v[224:227], v139 offset:39936
	global_load_lds_dwordx4 v[248:249], off
	v_lshl_add_u64 v[248:249], s[80:81], 0, v[130:131]
	s_mov_b32 m0, s72
	s_nop 0
	global_load_lds_dwordx4 v[248:249], off
	s_waitcnt vmcnt(8)
	s_waitcnt lgkmcnt(0)
	s_barrier
	s_waitcnt lgkmcnt(0)
	v_mfma_f32_16x16x32_bf16 v[124:127], v[160:163], v[196:199], v[124:127]
	v_mfma_f32_16x16x32_bf16 v[120:123], v[168:171], v[196:199], v[120:123]
	v_mfma_f32_16x16x32_bf16 v[116:119], v[160:163], v[204:207], v[116:119]
	v_mfma_f32_16x16x32_bf16 v[112:115], v[168:171], v[204:207], v[112:115]
	v_mfma_f32_16x16x32_bf16 v[100:103], v[160:163], v[212:215], v[100:103]
	v_mfma_f32_16x16x32_bf16 v[96:99], v[168:171], v[212:215], v[96:99]
	v_mfma_f32_16x16x32_bf16 v[84:87], v[160:163], v[220:223], v[84:87]
	v_mfma_f32_16x16x32_bf16 v[80:83], v[168:171], v[220:223], v[80:83]
	v_mfma_f32_16x16x32_bf16 v[124:127], v[164:167], v[200:203], v[124:127]
	v_mfma_f32_16x16x32_bf16 v[120:123], v[172:175], v[200:203], v[120:123]
	v_mfma_f32_16x16x32_bf16 v[116:119], v[164:167], v[208:211], v[116:119]
	v_mfma_f32_16x16x32_bf16 v[112:115], v[172:175], v[208:211], v[112:115]
	v_mfma_f32_16x16x32_bf16 v[100:103], v[164:167], v[216:219], v[100:103]
	v_mfma_f32_16x16x32_bf16 v[96:99], v[172:175], v[216:219], v[96:99]
	v_mfma_f32_16x16x32_bf16 v[84:87], v[164:167], v[224:227], v[84:87]
	v_mfma_f32_16x16x32_bf16 v[80:83], v[172:175], v[224:227], v[80:83]
	v_mfma_f32_16x16x32_bf16 v[108:111], v[180:183], v[196:199], v[108:111]
	v_mfma_f32_16x16x32_bf16 v[104:107], v[188:191], v[196:199], v[104:107]
	v_mfma_f32_16x16x32_bf16 v[92:95], v[180:183], v[204:207], v[92:95]
	v_mfma_f32_16x16x32_bf16 v[88:91], v[188:191], v[204:207], v[88:91]
	v_mfma_f32_16x16x32_bf16 v[76:79], v[180:183], v[212:215], v[76:79]
	v_mfma_f32_16x16x32_bf16 v[72:75], v[188:191], v[212:215], v[72:75]
	v_mfma_f32_16x16x32_bf16 v[68:71], v[180:183], v[220:223], v[68:71]
	v_mfma_f32_16x16x32_bf16 v[64:67], v[188:191], v[220:223], v[64:67]
	v_mfma_f32_16x16x32_bf16 v[108:111], v[184:187], v[200:203], v[108:111]
	v_mfma_f32_16x16x32_bf16 v[104:107], v[192:195], v[200:203], v[104:107]
	v_mfma_f32_16x16x32_bf16 v[92:95], v[184:187], v[208:211], v[92:95]
	v_mfma_f32_16x16x32_bf16 v[88:91], v[192:195], v[208:211], v[88:91]
	v_mfma_f32_16x16x32_bf16 v[76:79], v[184:187], v[216:219], v[76:79]
	v_mfma_f32_16x16x32_bf16 v[72:75], v[192:195], v[216:219], v[72:75]
	v_mfma_f32_16x16x32_bf16 v[68:71], v[184:187], v[224:227], v[68:71]
	v_mfma_f32_16x16x32_bf16 v[64:67], v[192:195], v[224:227], v[64:67]
	s_barrier
	s_add_i32 s17, s17, s3
	v_lshl_add_u64 v[228:229], v[228:229], 0, s[24:25]
	s_mov_b32 m0, s17
	ds_read_b128 v[196:199], v139 offset:49152
	ds_read_b128 v[200:203], v139 offset:50176
	ds_read_b128 v[204:207], v139 offset:51200
	ds_read_b128 v[208:211], v139 offset:52224
	ds_read_b128 v[212:215], v139 offset:53248
	ds_read_b128 v[216:219], v139 offset:54272
	ds_read_b128 v[220:223], v139 offset:55296
	ds_read_b128 v[224:227], v139 offset:56320
	global_load_lds_dwordx4 v[228:229], off
	v_lshl_add_u64 v[228:229], v[230:231], 0, s[24:25]
	s_add_i32 m0, s17, 0x2000
	s_add_i32 s17, s27, s3
	global_load_lds_dwordx4 v[228:229], off
	v_lshl_add_u64 v[228:229], v[232:233], 0, s[24:25]
	s_mov_b32 m0, s17
	s_nop 0
	global_load_lds_dwordx4 v[228:229], off
	v_lshl_add_u64 v[228:229], v[234:235], 0, s[24:25]
	s_add_i32 m0, s17, 0x2000
	s_nop 0
	global_load_lds_dwordx4 v[228:229], off
	v_lshl_add_u64 v[228:229], v[236:237], 0, s[24:25]
	s_mov_b32 m0, s73
	s_nop 0
	global_load_lds_dwordx4 v[228:229], off
	v_lshl_add_u64 v[228:229], v[246:247], 0, s[24:25]
	s_mov_b32 m0, s74
	s_nop 0
	global_load_lds_dwordx4 v[228:229], off
	s_waitcnt vmcnt(8)
	s_waitcnt lgkmcnt(0)
	s_barrier
; __device__ __forceinline__ unsigned cvt_pk_bf16(float lo, float hi) { const f32x2 v = {lo, hi}; return __builtin_bit_cast(unsigned, __builtin_convertvector(v, bf16x2_t)); }
; #define PG8_MMA(ai, bj, At, Bt) do { __builtin_amdgcn_s_setprio(1); _Pragma("unroll") for (int m = 0; m < 4; ++m) _Pragma("unroll") for (int n = 0; n < 2; ++n) _Pragma("unroll") for (int k = 0; k < 2; ++k) \
;         acc[ai][bj][m][n] = __builtin_amdgcn_mfma_f32_16x16x32_bf16(Bt[n][k], At[m][k], acc[ai][bj][m][n], 0, 0, 0); __builtin_amdgcn_s_setprio(0); } while (0)
; #define PG8_WAIT_V(n) asm volatile("s_waitcnt vmcnt(" #n ")" ::: "memory")
; #define PG8_WAIT_L(n) asm volatile("s_waitcnt lgkmcnt(" #n ")" ::: "memory")
; #define PG8_BAR __builtin_amdgcn_s_barrier()
; #define PG8_SCHED __builtin_amdgcn_sched_barrier(0)
;     template <class Sched> __device__ __forceinline__ void operator()(const f32x4 (&acc)[2][2][4][2], const Unit& u, const Sched& S, int wr, int wc, int fr, int fq) const {
;         const int rl0 = wr * 64 + fr, cl0 = wc * 32 + 8 * fq;
;         char* uo; int ldo, kind; S.out(u, uo, ldo, kind);
;         asm volatile("" : "+s"(ldo));
;         if (kind == 0) {
;             bf16_t* base = (bf16_t*)uo;
; #pragma unroll
;             for (int ai = 0; ai < 2; ++ai)
; #pragma unroll
;                 for (int m = 0; m < 4; ++m) { bf16_t* rowp = base + (size_t)(rl0 + ai * HALF + m * 16) * ldo + cl0;
; #pragma unroll
;                     for (int bj = 0; bj < 2; ++bj) { const f32x4 v0 = acc[ai][bj][m][0], v1 = acc[ai][bj][m][1];
;                         u32x4 w; w.x = cvt_pk_bf16(v0[0], v0[1]); w.y = cvt_pk_bf16(v0[2], v0[3]); w.z = cvt_pk_bf16(v1[0], v1[1]); w.w = cvt_pk_bf16(v1[2], v1[3]);
;                         *(u32x4*)(rowp + bj * HALF) = w; } }
; template <class Epi, class Sched, bool ALIGN_EPI>
; __device__ __forceinline__ void gemm_phase(LAS unsigned char* lds, const int wid, const int lda_, const int ldb_, const int K_, const Sched& S, const Epi& E) {
;     ...
;             PG8_WAIT_V(8); PG8_WAIT_L(0); PG8_BAR; PG8_MMA(1, 0, At, B0); PG8_MMA(1, 1, At, B1); PG8_BAR; PG8_SCHED;
;         }
;         if constexpr (ALIGN_EPI) { if (wr == 0) PG8_BAR; }
;         E(acc, cur, S, wr, wc, fr, fq);
;         if (!has_next) break;
	s_waitcnt lgkmcnt(0)
	v_mfma_f32_16x16x32_bf16 v[60:63], v[160:163], v[196:199], v[60:63]
	v_mfma_f32_16x16x32_bf16 v[56:59], v[168:171], v[196:199], v[56:59]
	v_mfma_f32_16x16x32_bf16 v[52:55], v[160:163], v[204:207], v[52:55]
	v_mfma_f32_16x16x32_bf16 v[48:51], v[168:171], v[204:207], v[48:51]
	v_mfma_f32_16x16x32_bf16 v[36:39], v[160:163], v[212:215], v[36:39]
	v_mfma_f32_16x16x32_bf16 v[32:35], v[168:171], v[212:215], v[32:35]
	v_mfma_f32_16x16x32_bf16 v[20:23], v[160:163], v[220:223], v[20:23]
	v_mfma_f32_16x16x32_bf16 v[16:19], v[168:171], v[220:223], v[16:19]
	v_mfma_f32_16x16x32_bf16 v[60:63], v[164:167], v[200:203], v[60:63]
	v_mfma_f32_16x16x32_bf16 v[56:59], v[172:175], v[200:203], v[56:59]
	v_mfma_f32_16x16x32_bf16 v[52:55], v[164:167], v[208:211], v[52:55]
	v_mfma_f32_16x16x32_bf16 v[48:51], v[172:175], v[208:211], v[48:51]
	v_mfma_f32_16x16x32_bf16 v[36:39], v[164:167], v[216:219], v[36:39]
	v_mfma_f32_16x16x32_bf16 v[32:35], v[172:175], v[216:219], v[32:35]
	v_mfma_f32_16x16x32_bf16 v[20:23], v[164:167], v[224:227], v[20:23]
	v_mfma_f32_16x16x32_bf16 v[16:19], v[172:175], v[224:227], v[16:19]
	v_mfma_f32_16x16x32_bf16 v[44:47], v[180:183], v[196:199], v[44:47]
	v_mfma_f32_16x16x32_bf16 v[40:43], v[188:191], v[196:199], v[40:43]
	v_mfma_f32_16x16x32_bf16 v[28:31], v[180:183], v[204:207], v[28:31]
	v_mfma_f32_16x16x32_bf16 v[24:27], v[188:191], v[204:207], v[24:27]
	v_mfma_f32_16x16x32_bf16 v[12:15], v[180:183], v[212:215], v[12:15]
	v_mfma_f32_16x16x32_bf16 v[8:11], v[188:191], v[212:215], v[8:11]
	v_mfma_f32_16x16x32_bf16 v[4:7], v[180:183], v[220:223], v[4:7]
	v_mfma_f32_16x16x32_bf16 v[0:3], v[188:191], v[220:223], v[0:3]
	v_mfma_f32_16x16x32_bf16 v[44:47], v[184:187], v[200:203], v[44:47]
	v_mfma_f32_16x16x32_bf16 v[40:43], v[192:195], v[200:203], v[40:43]
	v_mfma_f32_16x16x32_bf16 v[28:31], v[184:187], v[208:211], v[28:31]
	v_mfma_f32_16x16x32_bf16 v[24:27], v[192:195], v[208:211], v[24:27]
	v_mfma_f32_16x16x32_bf16 v[12:15], v[184:187], v[216:219], v[12:15]
	v_mfma_f32_16x16x32_bf16 v[8:11], v[192:195], v[216:219], v[8:11]
	v_mfma_f32_16x16x32_bf16 v[4:7], v[184:187], v[224:227], v[4:7]
	v_mfma_f32_16x16x32_bf16 v[0:3], v[192:195], v[224:227], v[0:3]
	s_barrier
	s_add_i32 s78, s78, 2
	s_add_u32 s50, s50, 0x100
	s_addc_u32 s51, s51, 0
	s_cmp_gt_u32 s78, 29
	s_cbranch_scc0 .LBB0_1120
	s_setprio 2
	s_and_b64 vcc, exec, s[36:37]
	s_cbranch_vccnz .Lepi_last_1120
	s_sub_i32 s4, s38, 22
	s_ashr_i32 s5, s38, 31
	s_cmp_lt_i32 s38, 22
	s_cselect_b32 s5, s5, 0
	s_cselect_b32 s4, s38, s4
	s_mov_b32 s17, 0x2bc00000
	s_cselect_b32 s17, 0x1f600000, s17
	s_lshl_b64 s[4:5], s[4:5], 9
	s_add_u32 s4, s66, s4
	s_addc_u32 s5, s67, s5
	s_add_u32 s4, s4, s17
	s_addc_u32 s5, s5, 0
	s_mul_i32 s27, s34, 0x2c0000
	s_mul_hi_i32 s17, s34, 0x2c0000
	s_add_u32 s4, s4, s27
	s_addc_u32 s5, s5, s17
	s_movk_i32 s17, 0x1600
	v_lshl_add_u64 v[156:157], v[136:137], 1, s[4:5]
	v_mad_i64_i32 v[158:159], s[4:5], s17, v134, 0
	v_lshl_add_u64 v[158:159], v[158:159], 1, v[156:157]
	v_cvt_pk_bf16_f32 v108, v108, v109
	v_cvt_pk_bf16_f32 v109, v110, v111
	v_cvt_pk_bf16_f32 v110, v104, v105
	v_cvt_pk_bf16_f32 v111, v106, v107
	v_mad_i64_i32 v[104:105], s[4:5], s17, v138, 0
	v_cvt_pk_bf16_f32 v124, v124, v125
	v_cvt_pk_bf16_f32 v125, v126, v127
	v_cvt_pk_bf16_f32 v126, v120, v121
	v_cvt_pk_bf16_f32 v127, v122, v123
	global_store_dwordx4 v[158:159], v[108:111], off offset:256
	v_cvt_pk_bf16_f32 v92, v92, v93
	v_cvt_pk_bf16_f32 v93, v94, v95
	v_lshl_add_u64 v[108:109], v[104:105], 1, v[156:157]
	v_cvt_pk_bf16_f32 v94, v88, v89
	v_cvt_pk_bf16_f32 v95, v90, v91
	v_mad_i64_i32 v[88:89], s[4:5], s17, v140, 0
	global_store_dwordx4 v[158:159], v[124:127], off
	v_cvt_pk_bf16_f32 v104, v116, v117
	v_cvt_pk_bf16_f32 v105, v118, v119
	v_cvt_pk_bf16_f32 v106, v112, v113
	v_cvt_pk_bf16_f32 v107, v114, v115
	global_store_dwordx4 v[108:109], v[92:95], off offset:256
	v_cvt_pk_bf16_f32 v76, v76, v77
	v_cvt_pk_bf16_f32 v77, v78, v79
	v_lshl_add_u64 v[92:93], v[88:89], 1, v[156:157]
	v_cvt_pk_bf16_f32 v78, v72, v73
	v_cvt_pk_bf16_f32 v79, v74, v75
	v_mad_i64_i32 v[72:73], s[4:5], s17, v142, 0
	v_cvt_pk_bf16_f32 v68, v68, v69
	v_cvt_pk_bf16_f32 v69, v70, v71
	v_cvt_pk_bf16_f32 v70, v64, v65
	v_mad_i64_i32 v[64:65], s[4:5], s17, v144, 0
	global_store_dwordx4 v[108:109], v[104:107], off
	v_cvt_pk_bf16_f32 v88, v100, v101
	v_cvt_pk_bf16_f32 v89, v102, v103
	v_cvt_pk_bf16_f32 v90, v96, v97
	v_cvt_pk_bf16_f32 v91, v98, v99
	global_store_dwordx4 v[92:93], v[76:79], off offset:256
	v_cvt_pk_bf16_f32 v74, v80, v81
	v_cvt_pk_bf16_f32 v75, v82, v83
	v_lshl_add_u64 v[76:77], v[72:73], 1, v[156:157]
	v_cvt_pk_bf16_f32 v72, v84, v85
	v_cvt_pk_bf16_f32 v73, v86, v87
	v_cvt_pk_bf16_f32 v71, v66, v67
	v_lshl_add_u64 v[64:65], v[64:65], 1, v[156:157]
	v_cvt_pk_bf16_f32 v44, v44, v45
	v_cvt_pk_bf16_f32 v45, v46, v47
	v_cvt_pk_bf16_f32 v46, v40, v41
	v_cvt_pk_bf16_f32 v47, v42, v43
	v_mad_i64_i32 v[40:41], s[4:5], s17, v146, 0
	global_store_dwordx4 v[92:93], v[88:91], off
	global_store_dwordx4 v[76:77], v[72:75], off
	global_store_dwordx4 v[76:77], v[68:71], off offset:256
	v_cvt_pk_bf16_f32 v60, v60, v61
	v_cvt_pk_bf16_f32 v61, v62, v63
	v_cvt_pk_bf16_f32 v62, v56, v57
	v_cvt_pk_bf16_f32 v63, v58, v59
	global_store_dwordx4 v[64:65], v[44:47], off offset:256
	v_cvt_pk_bf16_f32 v28, v28, v29
	v_cvt_pk_bf16_f32 v29, v30, v31
	v_lshl_add_u64 v[44:45], v[40:41], 1, v[156:157]
	v_cvt_pk_bf16_f32 v30, v24, v25
	v_cvt_pk_bf16_f32 v31, v26, v27
	v_mad_i64_i32 v[24:25], s[4:5], s17, v148, 0
	global_store_dwordx4 v[64:65], v[60:63], off
	v_cvt_pk_bf16_f32 v40, v52, v53
	v_cvt_pk_bf16_f32 v41, v54, v55
	v_cvt_pk_bf16_f32 v42, v48, v49
	v_cvt_pk_bf16_f32 v43, v50, v51
	global_store_dwordx4 v[44:45], v[28:31], off offset:256
	v_cvt_pk_bf16_f32 v12, v12, v13
	v_cvt_pk_bf16_f32 v13, v14, v15
	v_lshl_add_u64 v[28:29], v[24:25], 1, v[156:157]
	v_cvt_pk_bf16_f32 v14, v8, v9
	v_cvt_pk_bf16_f32 v15, v10, v11
	v_mad_i64_i32 v[8:9], s[4:5], s17, v150, 0
	global_store_dwordx4 v[44:45], v[40:43], off
	v_cvt_pk_bf16_f32 v24, v36, v37
	v_cvt_pk_bf16_f32 v25, v38, v39
	v_cvt_pk_bf16_f32 v26, v32, v33
	v_cvt_pk_bf16_f32 v27, v34, v35
	global_store_dwordx4 v[28:29], v[12:15], off offset:256
	v_cvt_pk_bf16_f32 v10, v16, v17
	v_cvt_pk_bf16_f32 v11, v18, v19
	v_lshl_add_u64 v[12:13], v[8:9], 1, v[156:157]
	v_cvt_pk_bf16_f32 v8, v20, v21
	v_cvt_pk_bf16_f32 v9, v22, v23
	v_cvt_pk_bf16_f32 v4, v4, v5
	v_cvt_pk_bf16_f32 v5, v6, v7
	v_cvt_pk_bf16_f32 v6, v0, v1
	v_cvt_pk_bf16_f32 v7, v2, v3
	s_and_b64 vcc, exec, s[36:37]
	s_mov_b32 s38, s42
	s_mov_b32 s34, s44
	s_mov_b64 s[50:51], s[48:49]
	s_mov_b64 s[40:41], s[46:47]
	global_store_dwordx4 v[28:29], v[24:27], off
	global_store_dwordx4 v[12:13], v[8:11], off
	global_store_dwordx4 v[12:13], v[4:7], off offset:256
	s_cbranch_vccz .LBB0_1117

; __device__ __forceinline__ unsigned cvt_pk_bf16(float lo, float hi) { const f32x2 v = {lo, hi}; return __builtin_bit_cast(unsigned, __builtin_convertvector(v, bf16x2_t)); }
;     template <class Sched> __device__ __forceinline__ void operator()(const f32x4 (&acc)[2][2][4][2], const Unit& u, const Sched& S, int wr, int wc, int fr, int fq) const {
;         const int rl0 = wr * 64 + fr, cl0 = wc * 32 + 8 * fq;
;         char* uo; int ldo, kind; S.out(u, uo, ldo, kind);
;         asm volatile("" : "+s"(ldo));
;         if (kind == 0) {
;             bf16_t* base = (bf16_t*)uo;
; #pragma unroll
;             for (int ai = 0; ai < 2; ++ai)
; #pragma unroll
;                 for (int m = 0; m < 4; ++m) { bf16_t* rowp = base + (size_t)(rl0 + ai * HALF + m * 16) * ldo + cl0;
; #pragma unroll
;                     for (int bj = 0; bj < 2; ++bj) { const f32x4 v0 = acc[ai][bj][m][0], v1 = acc[ai][bj][m][1];
;                         u32x4 w; w.x = cvt_pk_bf16(v0[0], v0[1]); w.y = cvt_pk_bf16(v0[2], v0[3]); w.z = cvt_pk_bf16(v1[0], v1[1]); w.w = cvt_pk_bf16(v1[2], v1[3]);
;                         *(u32x4*)(rowp + bj * HALF) = w; } }
.Lepi_last_1326:
	s_movk_i32 s17, 0x800
	v_lshl_add_u64 v[156:157], v[136:137], 1, s[4:5]
	v_mad_i64_i32 v[158:159], s[4:5], s17, v134, 0
	v_lshl_add_u64 v[158:159], v[158:159], 1, v[156:157]
	v_cvt_pk_bf16_f32 v108, v108, v109
	v_cvt_pk_bf16_f32 v109, v110, v111
	v_cvt_pk_bf16_f32 v110, v104, v105
	v_cvt_pk_bf16_f32 v111, v106, v107
	v_mad_i64_i32 v[104:105], s[4:5], s17, v138, 0
	v_cvt_pk_bf16_f32 v124, v124, v125
	v_cvt_pk_bf16_f32 v125, v126, v127
	v_cvt_pk_bf16_f32 v126, v120, v121
	v_cvt_pk_bf16_f32 v127, v122, v123
	global_store_dwordx4 v[158:159], v[108:111], off offset:256 sc1
	v_cvt_pk_bf16_f32 v92, v92, v93
	v_cvt_pk_bf16_f32 v93, v94, v95
	v_lshl_add_u64 v[108:109], v[104:105], 1, v[156:157]
	v_cvt_pk_bf16_f32 v94, v88, v89
	v_cvt_pk_bf16_f32 v95, v90, v91
	v_mad_i64_i32 v[88:89], s[4:5], s17, v140, 0
	global_store_dwordx4 v[158:159], v[124:127], off sc1
	v_cvt_pk_bf16_f32 v104, v116, v117
	v_cvt_pk_bf16_f32 v105, v118, v119
	v_cvt_pk_bf16_f32 v106, v112, v113
	v_cvt_pk_bf16_f32 v107, v114, v115
	global_store_dwordx4 v[108:109], v[92:95], off offset:256 sc1
	v_cvt_pk_bf16_f32 v76, v76, v77
	v_cvt_pk_bf16_f32 v77, v78, v79
	v_lshl_add_u64 v[92:93], v[88:89], 1, v[156:157]
	v_cvt_pk_bf16_f32 v78, v72, v73
	v_cvt_pk_bf16_f32 v79, v74, v75
	v_mad_i64_i32 v[72:73], s[4:5], s17, v142, 0
	v_cvt_pk_bf16_f32 v68, v68, v69
	v_cvt_pk_bf16_f32 v69, v70, v71
	v_cvt_pk_bf16_f32 v70, v64, v65
	v_mad_i64_i32 v[64:65], s[4:5], s17, v144, 0
	global_store_dwordx4 v[108:109], v[104:107], off sc1
	v_cvt_pk_bf16_f32 v88, v100, v101
	v_cvt_pk_bf16_f32 v89, v102, v103
	v_cvt_pk_bf16_f32 v90, v96, v97
	v_cvt_pk_bf16_f32 v91, v98, v99
	global_store_dwordx4 v[92:93], v[76:79], off offset:256 sc1
	v_cvt_pk_bf16_f32 v74, v80, v81
	v_cvt_pk_bf16_f32 v75, v82, v83
	v_lshl_add_u64 v[76:77], v[72:73], 1, v[156:157]
	v_cvt_pk_bf16_f32 v72, v84, v85
	v_cvt_pk_bf16_f32 v73, v86, v87
	v_cvt_pk_bf16_f32 v71, v66, v67
	v_lshl_add_u64 v[64:65], v[64:65], 1, v[156:157]
	v_cvt_pk_bf16_f32 v44, v44, v45
	v_cvt_pk_bf16_f32 v45, v46, v47
	v_cvt_pk_bf16_f32 v46, v40, v41
	v_cvt_pk_bf16_f32 v47, v42, v43
	v_mad_i64_i32 v[40:41], s[4:5], s17, v146, 0
	global_store_dwordx4 v[92:93], v[88:91], off sc1
	global_store_dwordx4 v[76:77], v[72:75], off sc1
	global_store_dwordx4 v[76:77], v[68:71], off offset:256 sc1
	v_cvt_pk_bf16_f32 v60, v60, v61
	v_cvt_pk_bf16_f32 v61, v62, v63
	v_cvt_pk_bf16_f32 v62, v56, v57
	v_cvt_pk_bf16_f32 v63, v58, v59
	global_store_dwordx4 v[64:65], v[44:47], off offset:256 sc1
	v_cvt_pk_bf16_f32 v28, v28, v29
	v_cvt_pk_bf16_f32 v29, v30, v31
	v_lshl_add_u64 v[44:45], v[40:41], 1, v[156:157]
	v_cvt_pk_bf16_f32 v30, v24, v25
	v_cvt_pk_bf16_f32 v31, v26, v27
	v_mad_i64_i32 v[24:25], s[4:5], s17, v148, 0
	global_store_dwordx4 v[64:65], v[60:63], off sc1
	v_cvt_pk_bf16_f32 v40, v52, v53
	v_cvt_pk_bf16_f32 v41, v54, v55
	v_cvt_pk_bf16_f32 v42, v48, v49
	v_cvt_pk_bf16_f32 v43, v50, v51
	global_store_dwordx4 v[44:45], v[28:31], off offset:256 sc1
	v_cvt_pk_bf16_f32 v12, v12, v13
	v_cvt_pk_bf16_f32 v13, v14, v15
	v_lshl_add_u64 v[28:29], v[24:25], 1, v[156:157]
	v_cvt_pk_bf16_f32 v14, v8, v9
	v_cvt_pk_bf16_f32 v15, v10, v11
	v_mad_i64_i32 v[8:9], s[4:5], s17, v150, 0
	global_store_dwordx4 v[44:45], v[40:43], off sc1
	v_cvt_pk_bf16_f32 v24, v36, v37
	v_cvt_pk_bf16_f32 v25, v38, v39
	v_cvt_pk_bf16_f32 v26, v32, v33
	v_cvt_pk_bf16_f32 v27, v34, v35
	global_store_dwordx4 v[28:29], v[12:15], off offset:256 sc1
	v_cvt_pk_bf16_f32 v10, v16, v17
	v_cvt_pk_bf16_f32 v11, v18, v19
	v_lshl_add_u64 v[12:13], v[8:9], 1, v[156:157]
	v_cvt_pk_bf16_f32 v8, v20, v21
	v_cvt_pk_bf16_f32 v9, v22, v23
	v_cvt_pk_bf16_f32 v4, v4, v5
	v_cvt_pk_bf16_f32 v5, v6, v7
	v_cvt_pk_bf16_f32 v6, v0, v1
	v_cvt_pk_bf16_f32 v7, v2, v3
	s_and_b64 vcc, exec, s[40:41]
	s_mov_b32 s38, s75
	s_mov_b32 s34, s73
	s_mov_b32 s30, s74
	s_mov_b64 s[48:49], s[36:37]
	s_mov_b64 s[46:47], s[42:43]
	global_store_dwordx4 v[28:29], v[24:27], off sc1
	global_store_dwordx4 v[12:13], v[8:11], off sc1
	global_store_dwordx4 v[12:13], v[4:7], off offset:256 sc1
	s_branch .LBB0_1346
; __device__ __forceinline__ unsigned cvt_pk_bf16(float lo, float hi) { const f32x2 v = {lo, hi}; return __builtin_bit_cast(unsigned, __builtin_convertvector(v, bf16x2_t)); }
;     template <class Sched> __device__ __forceinline__ void operator()(const f32x4 (&acc)[2][2][4][2], const Unit& u, const Sched& S, int wr, int wc, int fr, int fq) const {
;         const int rl0 = wr * 64 + fr, cl0 = wc * 32 + 8 * fq;
;         char* uo; int ldo, kind; S.out(u, uo, ldo, kind);
;         asm volatile("" : "+s"(ldo));
;         if (kind == 0) {
;             bf16_t* base = (bf16_t*)uo;
; #pragma unroll
;             for (int ai = 0; ai < 2; ++ai)
; #pragma unroll
;                 for (int m = 0; m < 4; ++m) { bf16_t* rowp = base + (size_t)(rl0 + ai * HALF + m * 16) * ldo + cl0;
; #pragma unroll
;                     for (int bj = 0; bj < 2; ++bj) { const f32x4 v0 = acc[ai][bj][m][0], v1 = acc[ai][bj][m][1];
;                         u32x4 w; w.x = cvt_pk_bf16(v0[0], v0[1]); w.y = cvt_pk_bf16(v0[2], v0[3]); w.z = cvt_pk_bf16(v1[0], v1[1]); w.w = cvt_pk_bf16(v1[2], v1[3]);
;                         *(u32x4*)(rowp + bj * HALF) = w; } }
; template <class Epi, class Sched, bool ALIGN_EPI>
; __device__ __forceinline__ void gemm_phase(LAS unsigned char* lds, const int wid, const int lda_, const int ldb_, const int K_, const Sched& S, const Epi& E) {
;     ...
;         E(acc, cur, S, wr, wc, fr, fq);
;         if (!has_next) break;
.LBB0_1326:
	s_and_b64 vcc, exec, s[40:41]
	s_cbranch_vccnz .Lepi_last_1326
	s_movk_i32 s17, 0x800
	v_lshl_add_u64 v[156:157], v[136:137], 1, s[4:5]
	v_mad_i64_i32 v[158:159], s[4:5], s17, v134, 0
	v_lshl_add_u64 v[158:159], v[158:159], 1, v[156:157]
	v_cvt_pk_bf16_f32 v108, v108, v109
	v_cvt_pk_bf16_f32 v109, v110, v111
	v_cvt_pk_bf16_f32 v110, v104, v105
	v_cvt_pk_bf16_f32 v111, v106, v107
	v_mad_i64_i32 v[104:105], s[4:5], s17, v138, 0
	v_cvt_pk_bf16_f32 v124, v124, v125
	v_cvt_pk_bf16_f32 v125, v126, v127
	v_cvt_pk_bf16_f32 v126, v120, v121
	v_cvt_pk_bf16_f32 v127, v122, v123
	global_store_dwordx4 v[158:159], v[108:111], off offset:256
	v_cvt_pk_bf16_f32 v92, v92, v93
	v_cvt_pk_bf16_f32 v93, v94, v95
	v_lshl_add_u64 v[108:109], v[104:105], 1, v[156:157]
	v_cvt_pk_bf16_f32 v94, v88, v89
	v_cvt_pk_bf16_f32 v95, v90, v91
	v_mad_i64_i32 v[88:89], s[4:5], s17, v140, 0
	global_store_dwordx4 v[158:159], v[124:127], off
	v_cvt_pk_bf16_f32 v104, v116, v117
	v_cvt_pk_bf16_f32 v105, v118, v119
	v_cvt_pk_bf16_f32 v106, v112, v113
	v_cvt_pk_bf16_f32 v107, v114, v115
	global_store_dwordx4 v[108:109], v[92:95], off offset:256
	v_cvt_pk_bf16_f32 v76, v76, v77
	v_cvt_pk_bf16_f32 v77, v78, v79
	v_lshl_add_u64 v[92:93], v[88:89], 1, v[156:157]
	v_cvt_pk_bf16_f32 v78, v72, v73
	v_cvt_pk_bf16_f32 v79, v74, v75
	v_mad_i64_i32 v[72:73], s[4:5], s17, v142, 0
	v_cvt_pk_bf16_f32 v68, v68, v69
	v_cvt_pk_bf16_f32 v69, v70, v71
	v_cvt_pk_bf16_f32 v70, v64, v65
	v_mad_i64_i32 v[64:65], s[4:5], s17, v144, 0
	global_store_dwordx4 v[108:109], v[104:107], off
	v_cvt_pk_bf16_f32 v88, v100, v101
	v_cvt_pk_bf16_f32 v89, v102, v103
	v_cvt_pk_bf16_f32 v90, v96, v97
	v_cvt_pk_bf16_f32 v91, v98, v99
	global_store_dwordx4 v[92:93], v[76:79], off offset:256
	v_cvt_pk_bf16_f32 v74, v80, v81
	v_cvt_pk_bf16_f32 v75, v82, v83
	v_lshl_add_u64 v[76:77], v[72:73], 1, v[156:157]
	v_cvt_pk_bf16_f32 v72, v84, v85
	v_cvt_pk_bf16_f32 v73, v86, v87
	v_cvt_pk_bf16_f32 v71, v66, v67
	v_lshl_add_u64 v[64:65], v[64:65], 1, v[156:157]
	v_cvt_pk_bf16_f32 v44, v44, v45
	v_cvt_pk_bf16_f32 v45, v46, v47
	v_cvt_pk_bf16_f32 v46, v40, v41
	v_cvt_pk_bf16_f32 v47, v42, v43
	v_mad_i64_i32 v[40:41], s[4:5], s17, v146, 0
	global_store_dwordx4 v[92:93], v[88:91], off
	global_store_dwordx4 v[76:77], v[72:75], off
	global_store_dwordx4 v[76:77], v[68:71], off offset:256
	v_cvt_pk_bf16_f32 v60, v60, v61
	v_cvt_pk_bf16_f32 v61, v62, v63
	v_cvt_pk_bf16_f32 v62, v56, v57
	v_cvt_pk_bf16_f32 v63, v58, v59
	global_store_dwordx4 v[64:65], v[44:47], off offset:256
	v_cvt_pk_bf16_f32 v28, v28, v29
	v_cvt_pk_bf16_f32 v29, v30, v31
	v_lshl_add_u64 v[44:45], v[40:41], 1, v[156:157]
	v_cvt_pk_bf16_f32 v30, v24, v25
	v_cvt_pk_bf16_f32 v31, v26, v27
	v_mad_i64_i32 v[24:25], s[4:5], s17, v148, 0
	global_store_dwordx4 v[64:65], v[60:63], off
	v_cvt_pk_bf16_f32 v40, v52, v53
	v_cvt_pk_bf16_f32 v41, v54, v55
	v_cvt_pk_bf16_f32 v42, v48, v49
	v_cvt_pk_bf16_f32 v43, v50, v51
	global_store_dwordx4 v[44:45], v[28:31], off offset:256
	v_cvt_pk_bf16_f32 v12, v12, v13
	v_cvt_pk_bf16_f32 v13, v14, v15
	v_lshl_add_u64 v[28:29], v[24:25], 1, v[156:157]
	v_cvt_pk_bf16_f32 v14, v8, v9
	v_cvt_pk_bf16_f32 v15, v10, v11
	v_mad_i64_i32 v[8:9], s[4:5], s17, v150, 0
	global_store_dwordx4 v[44:45], v[40:43], off
	v_cvt_pk_bf16_f32 v24, v36, v37
	v_cvt_pk_bf16_f32 v25, v38, v39
	v_cvt_pk_bf16_f32 v26, v32, v33
	v_cvt_pk_bf16_f32 v27, v34, v35
	global_store_dwordx4 v[28:29], v[12:15], off offset:256
	v_cvt_pk_bf16_f32 v10, v16, v17
	v_cvt_pk_bf16_f32 v11, v18, v19
	v_lshl_add_u64 v[12:13], v[8:9], 1, v[156:157]
	v_cvt_pk_bf16_f32 v8, v20, v21
	v_cvt_pk_bf16_f32 v9, v22, v23
	v_cvt_pk_bf16_f32 v4, v4, v5
	v_cvt_pk_bf16_f32 v5, v6, v7
	v_cvt_pk_bf16_f32 v6, v0, v1
	v_cvt_pk_bf16_f32 v7, v2, v3
	s_and_b64 vcc, exec, s[40:41]
	s_mov_b32 s38, s75
	s_mov_b32 s34, s73
	s_mov_b32 s30, s74
	s_mov_b64 s[48:49], s[36:37]
	s_mov_b64 s[46:47], s[42:43]
	global_store_dwordx4 v[28:29], v[24:27], off
	global_store_dwordx4 v[12:13], v[8:11], off
	global_store_dwordx4 v[12:13], v[4:7], off offset:256
	s_cbranch_vccnz .LBB0_1346
